# v52 + EpiResid K-slice-0 epilogue (w_o, mlp2): residual loads run 8 ahead in dead fragment registers instead of load-wait-store x16
# speedup vs baseline: 1.0104x; 1.0046x over previous
; #define GAS __attribute__((address_space(1)))
;     __device__ __forceinline__ void operator()(const f32x4 (&acc)[2][2][4][2], const Unit& u, int wr, int wc, int fr, int fq) const {
;         const int row0 = u.pm * BM + wr * 64 + fr, col0 = u.pn * BM + wc * 32 + 8 * fq;
;         const int bmod = u.pm < 4 ? 4 : ((u.pm - 4) >> 3);
;         const GAS float* gp = gate + (size_t)bmod * 12288;
;         f32x4 bv[2][2], gv[2][2];
; #pragma unroll
;         for (int bj = 0; bj < 2; ++bj)
; #pragma unroll
;             for (int n = 0; n < 2; ++n) { bv[bj][n] = *(const GAS f32x4*)(bias + col0 + bj * HALF + n * 4); gv[bj][n] = *(const GAS f32x4*)(gp + col0 + bj * HALF + n * 4); }
;         if (u.z == 0) {
; #pragma unroll
;             for (int ai = 0; ai < 2; ++ai)
; #pragma unroll
;                 for (int m = 0; m < 4; ++m) { const size_t off = (size_t)(row0 + ai * HALF + m * 16) * D + col0;
; #pragma unroll
;                     for (int bj = 0; bj < 2; ++bj) { f32x4 x0, x1; ldx8(X + off + bj * HALF, x0, x1);
;                         *(GAS f32x4*)(S + off + bj * HALF) = x0 * ALPHA + gv[bj][0] * (acc[ai][bj][m][0] + bv[bj][0]);
;                         *(GAS f32x4*)(S + off + bj * HALF + 4) = x1 * ALPHA + gv[bj][1] * (acc[ai][bj][m][1] + bv[bj][1]); } }
.LBB0_1311:
	v_lshlrev_b64 v[172:173], 11, v[176:177]
	v_lshl_add_u64 v[172:173], v[172:173], 0, v[174:175]
	v_lshl_add_u64 v[134:135], v[174:175], 2, s[44:45]
	v_lshl_add_u64 v[188:189], v[172:173], 1, s[22:23]
	global_load_dwordx4 v[122:125], v[134:135], off offset:528
	global_load_dwordx4 v[126:129], v[134:135], off offset:512
	global_load_dwordx4 v[130:133], v[134:135], off offset:16
	s_nop 0
	global_load_dwordx4 v[134:137], v[134:135], off
	s_mov_b64 s[4:5], 0x40000
	global_load_dwordx4 v[184:187], v[188:189], off
	s_waitcnt vmcnt(0)
	v_pk_add_f32 v[140:141], v[140:141], v[124:125]
	v_pk_add_f32 v[144:145], v[144:145], v[128:129]
	v_pk_add_f32 v[156:157], v[156:157], v[132:133]
	v_pk_add_f32 v[160:161], v[160:161], v[136:137]
	v_pk_add_f32 v[158:159], v[158:159], v[134:135]
	v_cvt_f32_f16_e32 v190, v185
	v_cvt_f32_f16_sdwa v191, v185 dst_sel:DWORD dst_unused:UNUSED_PAD src0_sel:WORD_1
	v_cvt_f32_f16_e32 v192, v184
	v_cvt_f32_f16_sdwa v193, v184 dst_sel:DWORD dst_unused:UNUSED_PAD src0_sel:WORD_1
	v_cvt_f32_f16_e32 v184, v187
	v_cvt_f32_f16_sdwa v185, v187 dst_sel:DWORD dst_unused:UNUSED_PAD src0_sel:WORD_1
	v_cvt_f32_f16_e32 v194, v186
	v_cvt_f32_f16_sdwa v195, v186 dst_sel:DWORD dst_unused:UNUSED_PAD src0_sel:WORD_1
	v_pk_mul_f32 v[186:187], v[192:193], s[66:67] op_sel_hi:[1,0]
	v_pk_mul_f32 v[190:191], v[190:191], s[66:67] op_sel_hi:[1,0]
	v_pk_fma_f32 v[158:159], v[102:103], v[158:159], v[186:187]
	v_pk_fma_f32 v[160:161], v[104:105], v[160:161], v[190:191]
	v_lshl_add_u64 v[186:187], v[172:173], 2, s[6:7]
	global_store_dwordx4 v[186:187], v[158:161], off
	v_pk_add_f32 v[154:155], v[154:155], v[130:131]
	v_pk_add_f32 v[142:143], v[142:143], v[126:127]
	v_pk_mul_f32 v[158:159], v[194:195], s[66:67] op_sel_hi:[1,0]
	v_pk_mul_f32 v[160:161], v[184:185], s[66:67] op_sel_hi:[1,0]
	v_pk_fma_f32 v[154:155], v[98:99], v[154:155], v[158:159]
	v_pk_fma_f32 v[156:157], v[100:101], v[156:157], v[160:161]
	global_store_dwordx4 v[186:187], v[154:157], off offset:16
	v_pk_add_f32 v[138:139], v[138:139], v[122:123]
	v_pk_add_f32 v[152:153], v[152:153], v[136:137]
	v_pk_add_f32 v[150:151], v[150:151], v[134:135]
	v_pk_add_f32 v[148:149], v[148:149], v[132:133]
	v_pk_add_f32 v[146:147], v[146:147], v[130:131]
	v_pk_add_f32 v[112:113], v[112:113], v[128:129]
	v_pk_add_f32 v[110:111], v[110:111], v[126:127]
	v_pk_add_f32 v[108:109], v[108:109], v[124:125]
	v_pk_add_f32 v[106:107], v[106:107], v[122:123]
	v_pk_add_f32 v[120:121], v[120:121], v[136:137]
	v_pk_add_f32 v[118:119], v[118:119], v[134:135]
	v_pk_add_f32 v[116:117], v[116:117], v[132:133]
	v_pk_add_f32 v[114:115], v[114:115], v[130:131]
	v_pk_add_f32 v[80:81], v[80:81], v[128:129]
	v_pk_add_f32 v[78:79], v[78:79], v[126:127]
	v_pk_add_f32 v[76:77], v[76:77], v[124:125]
	v_pk_add_f32 v[74:75], v[74:75], v[122:123]
	v_pk_add_f32 v[92:93], v[92:93], v[136:137]
	v_pk_add_f32 v[90:91], v[90:91], v[134:135]
	v_pk_add_f32 v[88:89], v[88:89], v[132:133]
	v_pk_add_f32 v[86:87], v[86:87], v[130:131]
	v_pk_add_f32 v[64:65], v[64:65], v[128:129]
	v_pk_add_f32 v[62:63], v[62:63], v[126:127]
	v_pk_add_f32 v[60:61], v[60:61], v[124:125]
	v_pk_add_f32 v[58:59], v[58:59], v[122:123]
	v_pk_add_f32 v[72:73], v[72:73], v[136:137]
	v_pk_add_f32 v[70:71], v[70:71], v[134:135]
	v_pk_add_f32 v[68:69], v[68:69], v[132:133]
	v_pk_add_f32 v[66:67], v[66:67], v[130:131]
	v_pk_add_f32 v[48:49], v[48:49], v[128:129]
	v_pk_add_f32 v[46:47], v[46:47], v[126:127]
	v_pk_add_f32 v[44:45], v[44:45], v[124:125]
	v_pk_add_f32 v[42:43], v[42:43], v[122:123]
	v_pk_add_f32 v[56:57], v[56:57], v[136:137]
	v_pk_add_f32 v[54:55], v[54:55], v[134:135]
	v_pk_add_f32 v[52:53], v[52:53], v[132:133]
	v_pk_add_f32 v[50:51], v[50:51], v[130:131]
	v_pk_add_f32 v[32:33], v[32:33], v[128:129]
	v_pk_add_f32 v[30:31], v[30:31], v[126:127]
	v_pk_add_f32 v[28:29], v[28:29], v[124:125]
	v_pk_add_f32 v[26:27], v[26:27], v[122:123]
	v_pk_add_f32 v[40:41], v[40:41], v[136:137]
	v_pk_add_f32 v[38:39], v[38:39], v[134:135]
	v_pk_add_f32 v[36:37], v[36:37], v[132:133]
	v_pk_add_f32 v[34:35], v[34:35], v[130:131]
	v_pk_add_f32 v[16:17], v[16:17], v[128:129]
	v_pk_add_f32 v[14:15], v[14:15], v[126:127]
	v_pk_add_f32 v[12:13], v[12:13], v[124:125]
	v_pk_add_f32 v[10:11], v[10:11], v[122:123]
	v_pk_add_f32 v[24:25], v[24:25], v[136:137]
	v_pk_add_f32 v[22:23], v[22:23], v[134:135]
	v_pk_add_f32 v[20:21], v[20:21], v[132:133]
	v_pk_add_f32 v[18:19], v[18:19], v[130:131]
	v_pk_add_f32 v[8:9], v[8:9], v[128:129]
	v_pk_add_f32 v[6:7], v[6:7], v[126:127]
	v_pk_add_f32 v[4:5], v[4:5], v[124:125]
	v_pk_add_f32 v[2:3], v[2:3], v[122:123]
	v_lshlrev_b32_e32 v188, 1, v172
	s_add_u32 s100, s22, 0x0
	s_addc_u32 s101, s23, 0
	global_load_dwordx4 v[124:127], v188, s[100:101] offset:256
	s_add_u32 s100, s22, 0x10000
	s_addc_u32 s101, s23, 0
	global_load_dwordx4 v[128:131], v188, s[100:101]
	s_add_u32 s100, s22, 0x10000
	s_addc_u32 s101, s23, 0
	global_load_dwordx4 v[132:135], v188, s[100:101] offset:256
	s_add_u32 s100, s22, 0x20000
	s_addc_u32 s101, s23, 0
	global_load_dwordx4 v[192:195], v188, s[100:101]
	s_add_u32 s100, s22, 0x20000
	s_addc_u32 s101, s23, 0
	global_load_dwordx4 v[196:199], v188, s[100:101] offset:256
	s_add_u32 s100, s22, 0x30000
	s_addc_u32 s101, s23, 0
	global_load_dwordx4 v[214:217], v188, s[100:101]
	s_add_u32 s100, s22, 0x30000
	s_addc_u32 s101, s23, 0
	global_load_dwordx4 v[218:221], v188, s[100:101] offset:256
	s_add_u32 s100, s22, 0x80000
	s_addc_u32 s101, s23, 0
	global_load_dwordx4 v[222:225], v188, s[100:101]
	s_waitcnt vmcnt(7)
; #define GAS __attribute__((address_space(1)))
; __device__ __forceinline__ void ldx8(const GAS f16_t* p, f32x4& lo, f32x4& hi) { const f16x8 h = *(const GAS f16x8*)p;
;     lo = __builtin_convertvector(__builtin_shufflevector(h, h, 0, 1, 2, 3), f32x4); hi = __builtin_convertvector(__builtin_shufflevector(h, h, 4, 5, 6, 7), f32x4); }
;     __device__ __forceinline__ void operator()(const f32x4 (&acc)[2][2][4][2], const Unit& u, int wr, int wc, int fr, int fq) const {
;     ...
;                 for (int m = 0; m < 4; ++m) { const size_t off = (size_t)(row0 + ai * HALF + m * 16) * D + col0;
; #pragma unroll
;                     for (int bj = 0; bj < 2; ++bj) { f32x4 x0, x1; ldx8(X + off + bj * HALF, x0, x1);
;                         *(GAS f32x4*)(S + off + bj * HALF) = x0 * ALPHA + gv[bj][0] * (acc[ai][bj][m][0] + bv[bj][0]);
;                         *(GAS f32x4*)(S + off + bj * HALF + 4) = x1 * ALPHA + gv[bj][1] * (acc[ai][bj][m][1] + bv[bj][1]); } }
	v_cvt_f32_f16_e32 v158, v125
	v_cvt_f32_f16_sdwa v159, v125 dst_sel:DWORD dst_unused:UNUSED_PAD src0_sel:WORD_1
	v_cvt_f32_f16_e32 v160, v124
	v_cvt_f32_f16_sdwa v161, v124 dst_sel:DWORD dst_unused:UNUSED_PAD src0_sel:WORD_1
	v_cvt_f32_f16_e32 v154, v127
	v_cvt_f32_f16_sdwa v155, v127 dst_sel:DWORD dst_unused:UNUSED_PAD src0_sel:WORD_1
	v_cvt_f32_f16_e32 v184, v126
	v_cvt_f32_f16_sdwa v185, v126 dst_sel:DWORD dst_unused:UNUSED_PAD src0_sel:WORD_1
	v_pk_mul_f32 v[156:157], v[160:161], s[66:67] op_sel_hi:[1,0]
	v_pk_mul_f32 v[158:159], v[158:159], s[66:67] op_sel_hi:[1,0]
	v_pk_fma_f32 v[142:143], v[94:95], v[142:143], v[156:157]
	v_pk_fma_f32 v[144:145], v[96:97], v[144:145], v[158:159]
	global_store_dwordx4 v[186:187], v[142:145], off offset:512
	s_nop 1
	v_pk_mul_f32 v[142:143], v[184:185], s[66:67] op_sel_hi:[1,0]
	v_pk_mul_f32 v[144:145], v[154:155], s[66:67] op_sel_hi:[1,0]
	v_pk_fma_f32 v[138:139], v[82:83], v[138:139], v[142:143]
	v_pk_fma_f32 v[140:141], v[84:85], v[140:141], v[144:145]
	global_store_dwordx4 v[186:187], v[138:141], off offset:528
	s_nop 1
	v_or_b32_e32 v138, 16, v176
	v_ashrrev_i32_e32 v139, 31, v138
	v_lshlrev_b64 v[138:139], 11, v[138:139]
	v_lshl_add_u64 v[144:145], v[138:139], 0, v[174:175]
	v_lshl_add_u64 v[138:139], v[144:145], 1, s[22:23]
	s_add_u32 s100, s22, 0x80000
	s_addc_u32 s101, s23, 0
	global_load_dwordx4 v[124:127], v188, s[100:101] offset:256
	v_lshl_add_u64 v[144:145], v[144:145], 2, s[6:7]
	s_waitcnt vmcnt(9)
	v_cvt_f32_f16_e32 v154, v129
	v_cvt_f32_f16_sdwa v155, v129 dst_sel:DWORD dst_unused:UNUSED_PAD src0_sel:WORD_1
	v_cvt_f32_f16_e32 v156, v128
	v_cvt_f32_f16_sdwa v157, v128 dst_sel:DWORD dst_unused:UNUSED_PAD src0_sel:WORD_1
	v_cvt_f32_f16_e32 v158, v131
	v_cvt_f32_f16_sdwa v159, v131 dst_sel:DWORD dst_unused:UNUSED_PAD src0_sel:WORD_1
	v_cvt_f32_f16_e32 v160, v130
	v_cvt_f32_f16_sdwa v161, v130 dst_sel:DWORD dst_unused:UNUSED_PAD src0_sel:WORD_1
	v_pk_mul_f32 v[140:141], v[156:157], s[66:67] op_sel_hi:[1,0]
	v_pk_mul_f32 v[142:143], v[154:155], s[66:67] op_sel_hi:[1,0]
	v_pk_fma_f32 v[140:141], v[102:103], v[150:151], v[140:141]
	v_pk_fma_f32 v[142:143], v[104:105], v[152:153], v[142:143]
	global_store_dwordx4 v[144:145], v[140:143], off
	s_nop 1
	v_pk_mul_f32 v[140:141], v[160:161], s[66:67] op_sel_hi:[1,0]
	v_pk_mul_f32 v[142:143], v[158:159], s[66:67] op_sel_hi:[1,0]
	v_pk_fma_f32 v[140:141], v[98:99], v[146:147], v[140:141]
	v_pk_fma_f32 v[142:143], v[100:101], v[148:149], v[142:143]
	global_store_dwordx4 v[144:145], v[140:143], off offset:16
	s_add_u32 s100, s22, 0x90000
	s_addc_u32 s101, s23, 0
	global_load_dwordx4 v[128:131], v188, s[100:101]
	s_waitcnt vmcnt(11)
	v_cvt_f32_f16_e32 v146, v132
	v_cvt_f32_f16_e32 v142, v133
	v_cvt_f32_f16_sdwa v143, v133 dst_sel:DWORD dst_unused:UNUSED_PAD src0_sel:WORD_1
	v_cvt_f32_f16_sdwa v147, v132 dst_sel:DWORD dst_unused:UNUSED_PAD src0_sel:WORD_1
	v_cvt_f32_f16_e32 v138, v135
	v_cvt_f32_f16_sdwa v139, v135 dst_sel:DWORD dst_unused:UNUSED_PAD src0_sel:WORD_1
	v_cvt_f32_f16_e32 v148, v134
	v_cvt_f32_f16_sdwa v149, v134 dst_sel:DWORD dst_unused:UNUSED_PAD src0_sel:WORD_1
	v_pk_mul_f32 v[140:141], v[146:147], s[66:67] op_sel_hi:[1,0]
	v_pk_mul_f32 v[142:143], v[142:143], s[66:67] op_sel_hi:[1,0]
	v_pk_fma_f32 v[110:111], v[94:95], v[110:111], v[140:141]
	v_pk_fma_f32 v[112:113], v[96:97], v[112:113], v[142:143]
	global_store_dwordx4 v[144:145], v[110:113], off offset:512
	s_nop 1
	v_pk_mul_f32 v[110:111], v[148:149], s[66:67] op_sel_hi:[1,0]
	v_pk_mul_f32 v[112:113], v[138:139], s[66:67] op_sel_hi:[1,0]
	v_pk_fma_f32 v[106:107], v[82:83], v[106:107], v[110:111]
	v_pk_fma_f32 v[108:109], v[84:85], v[108:109], v[112:113]
	global_store_dwordx4 v[144:145], v[106:109], off offset:528
	s_nop 1
	v_or_b32_e32 v106, 32, v176
	v_ashrrev_i32_e32 v107, 31, v106
	v_lshlrev_b64 v[106:107], 11, v[106:107]
	v_lshl_add_u64 v[112:113], v[106:107], 0, v[174:175]
	v_lshl_add_u64 v[106:107], v[112:113], 1, s[22:23]
	s_add_u32 s100, s22, 0x90000
	s_addc_u32 s101, s23, 0
	global_load_dwordx4 v[132:135], v188, s[100:101] offset:256
	v_lshl_add_u64 v[112:113], v[112:113], 2, s[6:7]
	s_waitcnt vmcnt(13)
	v_cvt_f32_f16_e32 v138, v193
	v_cvt_f32_f16_sdwa v139, v193 dst_sel:DWORD dst_unused:UNUSED_PAD src0_sel:WORD_1
	v_cvt_f32_f16_e32 v140, v192
	v_cvt_f32_f16_sdwa v141, v192 dst_sel:DWORD dst_unused:UNUSED_PAD src0_sel:WORD_1
	v_cvt_f32_f16_e32 v142, v195
	v_cvt_f32_f16_sdwa v143, v195 dst_sel:DWORD dst_unused:UNUSED_PAD src0_sel:WORD_1
	v_cvt_f32_f16_e32 v144, v194
	v_cvt_f32_f16_sdwa v145, v194 dst_sel:DWORD dst_unused:UNUSED_PAD src0_sel:WORD_1
	v_pk_mul_f32 v[108:109], v[140:141], s[66:67] op_sel_hi:[1,0]
	v_pk_mul_f32 v[110:111], v[138:139], s[66:67] op_sel_hi:[1,0]
	v_pk_fma_f32 v[108:109], v[102:103], v[118:119], v[108:109]
	v_pk_fma_f32 v[110:111], v[104:105], v[120:121], v[110:111]
	global_store_dwordx4 v[112:113], v[108:111], off
	s_nop 1
	v_pk_mul_f32 v[108:109], v[144:145], s[66:67] op_sel_hi:[1,0]
	v_pk_mul_f32 v[110:111], v[142:143], s[66:67] op_sel_hi:[1,0]
	v_pk_fma_f32 v[108:109], v[98:99], v[114:115], v[108:109]
	v_pk_fma_f32 v[110:111], v[100:101], v[116:117], v[110:111]
	global_store_dwordx4 v[112:113], v[108:111], off offset:16
	s_add_u32 s100, s22, 0xa0000
	s_addc_u32 s101, s23, 0
	global_load_dwordx4 v[192:195], v188, s[100:101]
	s_waitcnt vmcnt(15)
; #define GAS __attribute__((address_space(1)))
; __device__ __forceinline__ void ldx8(const GAS f16_t* p, f32x4& lo, f32x4& hi) { const f16x8 h = *(const GAS f16x8*)p;
;     lo = __builtin_convertvector(__builtin_shufflevector(h, h, 0, 1, 2, 3), f32x4); hi = __builtin_convertvector(__builtin_shufflevector(h, h, 4, 5, 6, 7), f32x4); }
;     __device__ __forceinline__ void operator()(const f32x4 (&acc)[2][2][4][2], const Unit& u, int wr, int wc, int fr, int fq) const {
;     ...
;                 for (int m = 0; m < 4; ++m) { const size_t off = (size_t)(row0 + ai * HALF + m * 16) * D + col0;
; #pragma unroll
;                     for (int bj = 0; bj < 2; ++bj) { f32x4 x0, x1; ldx8(X + off + bj * HALF, x0, x1);
;                         *(GAS f32x4*)(S + off + bj * HALF) = x0 * ALPHA + gv[bj][0] * (acc[ai][bj][m][0] + bv[bj][0]);
;                         *(GAS f32x4*)(S + off + bj * HALF + 4) = x1 * ALPHA + gv[bj][1] * (acc[ai][bj][m][1] + bv[bj][1]); } }
	v_cvt_f32_f16_e32 v114, v196
	v_cvt_f32_f16_e32 v110, v197
	v_cvt_f32_f16_sdwa v111, v197 dst_sel:DWORD dst_unused:UNUSED_PAD src0_sel:WORD_1
	v_cvt_f32_f16_sdwa v115, v196 dst_sel:DWORD dst_unused:UNUSED_PAD src0_sel:WORD_1
	v_cvt_f32_f16_e32 v106, v199
	v_cvt_f32_f16_sdwa v107, v199 dst_sel:DWORD dst_unused:UNUSED_PAD src0_sel:WORD_1
	v_cvt_f32_f16_e32 v116, v198
	v_cvt_f32_f16_sdwa v117, v198 dst_sel:DWORD dst_unused:UNUSED_PAD src0_sel:WORD_1
	v_pk_mul_f32 v[108:109], v[114:115], s[66:67] op_sel_hi:[1,0]
	v_pk_mul_f32 v[110:111], v[110:111], s[66:67] op_sel_hi:[1,0]
	v_pk_fma_f32 v[78:79], v[94:95], v[78:79], v[108:109]
	v_pk_fma_f32 v[80:81], v[96:97], v[80:81], v[110:111]
	global_store_dwordx4 v[112:113], v[78:81], off offset:512
	s_nop 1
	v_pk_mul_f32 v[78:79], v[116:117], s[66:67] op_sel_hi:[1,0]
	v_pk_mul_f32 v[80:81], v[106:107], s[66:67] op_sel_hi:[1,0]
	v_pk_fma_f32 v[74:75], v[82:83], v[74:75], v[78:79]
	v_pk_fma_f32 v[76:77], v[84:85], v[76:77], v[80:81]
	global_store_dwordx4 v[112:113], v[74:77], off offset:528
	s_nop 1
	v_or_b32_e32 v74, 48, v176
	v_ashrrev_i32_e32 v75, 31, v74
	v_lshlrev_b64 v[74:75], 11, v[74:75]
	v_lshl_add_u64 v[80:81], v[74:75], 0, v[174:175]
	v_lshl_add_u64 v[74:75], v[80:81], 1, s[22:23]
	s_add_u32 s100, s22, 0xa0000
	s_addc_u32 s101, s23, 0
	global_load_dwordx4 v[196:199], v188, s[100:101] offset:256
	v_lshl_add_u64 v[80:81], v[80:81], 2, s[6:7]
	s_waitcnt vmcnt(17)
	v_cvt_f32_f16_e32 v106, v215
	v_cvt_f32_f16_sdwa v107, v215 dst_sel:DWORD dst_unused:UNUSED_PAD src0_sel:WORD_1
	v_cvt_f32_f16_e32 v108, v214
	v_cvt_f32_f16_sdwa v109, v214 dst_sel:DWORD dst_unused:UNUSED_PAD src0_sel:WORD_1
	v_cvt_f32_f16_e32 v110, v217
	v_cvt_f32_f16_sdwa v111, v217 dst_sel:DWORD dst_unused:UNUSED_PAD src0_sel:WORD_1
	v_cvt_f32_f16_e32 v112, v216
	v_cvt_f32_f16_sdwa v113, v216 dst_sel:DWORD dst_unused:UNUSED_PAD src0_sel:WORD_1
	v_pk_mul_f32 v[76:77], v[108:109], s[66:67] op_sel_hi:[1,0]
	v_pk_mul_f32 v[78:79], v[106:107], s[66:67] op_sel_hi:[1,0]
	v_pk_fma_f32 v[76:77], v[102:103], v[90:91], v[76:77]
	v_pk_fma_f32 v[78:79], v[104:105], v[92:93], v[78:79]
	global_store_dwordx4 v[80:81], v[76:79], off
	s_nop 1
	v_pk_mul_f32 v[76:77], v[112:113], s[66:67] op_sel_hi:[1,0]
	v_pk_mul_f32 v[78:79], v[110:111], s[66:67] op_sel_hi:[1,0]
	v_pk_fma_f32 v[76:77], v[98:99], v[86:87], v[76:77]
	v_pk_fma_f32 v[78:79], v[100:101], v[88:89], v[78:79]
	global_store_dwordx4 v[80:81], v[76:79], off offset:16
	s_add_u32 s100, s22, 0xb0000
	s_addc_u32 s101, s23, 0
	global_load_dwordx4 v[214:217], v188, s[100:101]
	s_waitcnt vmcnt(19)
	v_cvt_f32_f16_e32 v86, v218
	v_cvt_f32_f16_e32 v78, v219
	v_cvt_f32_f16_sdwa v79, v219 dst_sel:DWORD dst_unused:UNUSED_PAD src0_sel:WORD_1
	v_cvt_f32_f16_sdwa v87, v218 dst_sel:DWORD dst_unused:UNUSED_PAD src0_sel:WORD_1
	v_cvt_f32_f16_e32 v74, v221
	v_cvt_f32_f16_sdwa v75, v221 dst_sel:DWORD dst_unused:UNUSED_PAD src0_sel:WORD_1
	v_cvt_f32_f16_e32 v88, v220
	v_cvt_f32_f16_sdwa v89, v220 dst_sel:DWORD dst_unused:UNUSED_PAD src0_sel:WORD_1
	v_pk_mul_f32 v[76:77], v[86:87], s[66:67] op_sel_hi:[1,0]
	v_pk_mul_f32 v[78:79], v[78:79], s[66:67] op_sel_hi:[1,0]
	v_pk_fma_f32 v[62:63], v[94:95], v[62:63], v[76:77]
	v_pk_fma_f32 v[64:65], v[96:97], v[64:65], v[78:79]
	global_store_dwordx4 v[80:81], v[62:65], off offset:512
	s_nop 1
	v_pk_mul_f32 v[62:63], v[88:89], s[66:67] op_sel_hi:[1,0]
	v_pk_mul_f32 v[64:65], v[74:75], s[66:67] op_sel_hi:[1,0]
	v_pk_fma_f32 v[58:59], v[82:83], v[58:59], v[62:63]
	v_pk_fma_f32 v[60:61], v[84:85], v[60:61], v[64:65]
	v_lshl_add_u64 v[64:65], v[172:173], 0, s[4:5]
	global_store_dwordx4 v[80:81], v[58:61], off offset:528
	s_mov_b64 s[4:5], 0x48000
	s_nop 0
	v_lshl_add_u64 v[58:59], v[64:65], 1, s[22:23]
	s_add_u32 s100, s22, 0xb0000
	s_addc_u32 s101, s23, 0
	global_load_dwordx4 v[218:221], v188, s[100:101] offset:256
	v_lshl_add_u64 v[64:65], v[64:65], 2, s[6:7]
	s_waitcnt vmcnt(21)
	v_cvt_f32_f16_e32 v74, v223
	v_cvt_f32_f16_sdwa v75, v223 dst_sel:DWORD dst_unused:UNUSED_PAD src0_sel:WORD_1
	v_cvt_f32_f16_e32 v76, v222
	v_cvt_f32_f16_sdwa v77, v222 dst_sel:DWORD dst_unused:UNUSED_PAD src0_sel:WORD_1
	v_cvt_f32_f16_e32 v78, v225
	v_cvt_f32_f16_sdwa v79, v225 dst_sel:DWORD dst_unused:UNUSED_PAD src0_sel:WORD_1
	v_cvt_f32_f16_e32 v80, v224
	v_cvt_f32_f16_sdwa v81, v224 dst_sel:DWORD dst_unused:UNUSED_PAD src0_sel:WORD_1
	v_pk_mul_f32 v[60:61], v[76:77], s[66:67] op_sel_hi:[1,0]
	v_pk_mul_f32 v[62:63], v[74:75], s[66:67] op_sel_hi:[1,0]
	v_pk_fma_f32 v[60:61], v[102:103], v[70:71], v[60:61]
	v_pk_fma_f32 v[62:63], v[104:105], v[72:73], v[62:63]
	global_store_dwordx4 v[64:65], v[60:63], off
	s_nop 1
	v_pk_mul_f32 v[60:61], v[80:81], s[66:67] op_sel_hi:[1,0]
	v_pk_mul_f32 v[62:63], v[78:79], s[66:67] op_sel_hi:[1,0]
	v_pk_fma_f32 v[60:61], v[98:99], v[66:67], v[60:61]
	v_pk_fma_f32 v[62:63], v[100:101], v[68:69], v[62:63]
	global_store_dwordx4 v[64:65], v[60:63], off offset:16
	s_waitcnt vmcnt(20)
	v_cvt_f32_f16_e32 v66, v124
	v_cvt_f32_f16_e32 v62, v125
	v_cvt_f32_f16_sdwa v63, v125 dst_sel:DWORD dst_unused:UNUSED_PAD src0_sel:WORD_1
	v_cvt_f32_f16_sdwa v67, v124 dst_sel:DWORD dst_unused:UNUSED_PAD src0_sel:WORD_1
	v_cvt_f32_f16_e32 v58, v127
	v_cvt_f32_f16_sdwa v59, v127 dst_sel:DWORD dst_unused:UNUSED_PAD src0_sel:WORD_1
	v_cvt_f32_f16_e32 v68, v126
	v_cvt_f32_f16_sdwa v69, v126 dst_sel:DWORD dst_unused:UNUSED_PAD src0_sel:WORD_1
	v_pk_mul_f32 v[60:61], v[66:67], s[66:67] op_sel_hi:[1,0]
	v_pk_mul_f32 v[62:63], v[62:63], s[66:67] op_sel_hi:[1,0]
	v_pk_fma_f32 v[46:47], v[94:95], v[46:47], v[60:61]
	v_pk_fma_f32 v[48:49], v[96:97], v[48:49], v[62:63]
	global_store_dwordx4 v[64:65], v[46:49], off offset:512
	s_nop 1
	v_pk_mul_f32 v[46:47], v[68:69], s[66:67] op_sel_hi:[1,0]
	v_pk_mul_f32 v[48:49], v[58:59], s[66:67] op_sel_hi:[1,0]
	v_pk_fma_f32 v[42:43], v[82:83], v[42:43], v[46:47]
	v_pk_fma_f32 v[44:45], v[84:85], v[44:45], v[48:49]
	v_lshl_add_u64 v[48:49], v[172:173], 0, s[4:5]
	global_store_dwordx4 v[64:65], v[42:45], off offset:528
	s_mov_b64 s[4:5], 0x50000
	s_nop 0
	v_lshl_add_u64 v[42:43], v[48:49], 1, s[22:23]
	v_lshl_add_u64 v[48:49], v[48:49], 2, s[6:7]
	s_waitcnt vmcnt(19)
; #define GAS __attribute__((address_space(1)))
; __device__ __forceinline__ void ldx8(const GAS f16_t* p, f32x4& lo, f32x4& hi) { const f16x8 h = *(const GAS f16x8*)p;
;     lo = __builtin_convertvector(__builtin_shufflevector(h, h, 0, 1, 2, 3), f32x4); hi = __builtin_convertvector(__builtin_shufflevector(h, h, 4, 5, 6, 7), f32x4); }
;     __device__ __forceinline__ void operator()(const f32x4 (&acc)[2][2][4][2], const Unit& u, int wr, int wc, int fr, int fq) const {
;     ...
;                 for (int m = 0; m < 4; ++m) { const size_t off = (size_t)(row0 + ai * HALF + m * 16) * D + col0;
; #pragma unroll
;                     for (int bj = 0; bj < 2; ++bj) { f32x4 x0, x1; ldx8(X + off + bj * HALF, x0, x1);
;                         *(GAS f32x4*)(S + off + bj * HALF) = x0 * ALPHA + gv[bj][0] * (acc[ai][bj][m][0] + bv[bj][0]);
;                         *(GAS f32x4*)(S + off + bj * HALF + 4) = x1 * ALPHA + gv[bj][1] * (acc[ai][bj][m][1] + bv[bj][1]); } }
	v_cvt_f32_f16_e32 v58, v129
	v_cvt_f32_f16_sdwa v59, v129 dst_sel:DWORD dst_unused:UNUSED_PAD src0_sel:WORD_1
	v_cvt_f32_f16_e32 v60, v128
	v_cvt_f32_f16_sdwa v61, v128 dst_sel:DWORD dst_unused:UNUSED_PAD src0_sel:WORD_1
	v_cvt_f32_f16_e32 v62, v131
	v_cvt_f32_f16_sdwa v63, v131 dst_sel:DWORD dst_unused:UNUSED_PAD src0_sel:WORD_1
	v_cvt_f32_f16_e32 v64, v130
	v_cvt_f32_f16_sdwa v65, v130 dst_sel:DWORD dst_unused:UNUSED_PAD src0_sel:WORD_1
	v_pk_mul_f32 v[44:45], v[60:61], s[66:67] op_sel_hi:[1,0]
	v_pk_mul_f32 v[46:47], v[58:59], s[66:67] op_sel_hi:[1,0]
	v_pk_fma_f32 v[44:45], v[102:103], v[54:55], v[44:45]
	v_pk_fma_f32 v[46:47], v[104:105], v[56:57], v[46:47]
	global_store_dwordx4 v[48:49], v[44:47], off
	s_nop 1
	v_pk_mul_f32 v[44:45], v[64:65], s[66:67] op_sel_hi:[1,0]
	v_pk_mul_f32 v[46:47], v[62:63], s[66:67] op_sel_hi:[1,0]
	v_pk_fma_f32 v[44:45], v[98:99], v[50:51], v[44:45]
	v_pk_fma_f32 v[46:47], v[100:101], v[52:53], v[46:47]
	global_store_dwordx4 v[48:49], v[44:47], off offset:16
	s_waitcnt vmcnt(18)
	v_cvt_f32_f16_e32 v50, v132
	v_cvt_f32_f16_e32 v46, v133
	v_cvt_f32_f16_sdwa v47, v133 dst_sel:DWORD dst_unused:UNUSED_PAD src0_sel:WORD_1
	v_cvt_f32_f16_sdwa v51, v132 dst_sel:DWORD dst_unused:UNUSED_PAD src0_sel:WORD_1
	v_cvt_f32_f16_e32 v42, v135
	v_cvt_f32_f16_sdwa v43, v135 dst_sel:DWORD dst_unused:UNUSED_PAD src0_sel:WORD_1
	v_cvt_f32_f16_e32 v52, v134
	v_cvt_f32_f16_sdwa v53, v134 dst_sel:DWORD dst_unused:UNUSED_PAD src0_sel:WORD_1
	v_pk_mul_f32 v[44:45], v[50:51], s[66:67] op_sel_hi:[1,0]
	v_pk_mul_f32 v[46:47], v[46:47], s[66:67] op_sel_hi:[1,0]
	v_pk_fma_f32 v[30:31], v[94:95], v[30:31], v[44:45]
	v_pk_fma_f32 v[32:33], v[96:97], v[32:33], v[46:47]
	global_store_dwordx4 v[48:49], v[30:33], off offset:512
	s_nop 1
	v_pk_mul_f32 v[30:31], v[52:53], s[66:67] op_sel_hi:[1,0]
	v_pk_mul_f32 v[32:33], v[42:43], s[66:67] op_sel_hi:[1,0]
	v_pk_fma_f32 v[26:27], v[82:83], v[26:27], v[30:31]
	v_pk_fma_f32 v[28:29], v[84:85], v[28:29], v[32:33]
	v_lshl_add_u64 v[32:33], v[172:173], 0, s[4:5]
	global_store_dwordx4 v[48:49], v[26:29], off offset:528
	s_mov_b64 s[4:5], 0x58000
	s_nop 0
	v_lshl_add_u64 v[26:27], v[32:33], 1, s[22:23]
	v_lshl_add_u64 v[32:33], v[32:33], 2, s[6:7]
	s_waitcnt vmcnt(17)
	v_cvt_f32_f16_e32 v42, v193
	v_cvt_f32_f16_sdwa v43, v193 dst_sel:DWORD dst_unused:UNUSED_PAD src0_sel:WORD_1
	v_cvt_f32_f16_e32 v44, v192
	v_cvt_f32_f16_sdwa v45, v192 dst_sel:DWORD dst_unused:UNUSED_PAD src0_sel:WORD_1
	v_cvt_f32_f16_e32 v46, v195
	v_cvt_f32_f16_sdwa v47, v195 dst_sel:DWORD dst_unused:UNUSED_PAD src0_sel:WORD_1
	v_cvt_f32_f16_e32 v48, v194
	v_cvt_f32_f16_sdwa v49, v194 dst_sel:DWORD dst_unused:UNUSED_PAD src0_sel:WORD_1
	v_pk_mul_f32 v[28:29], v[44:45], s[66:67] op_sel_hi:[1,0]
	v_pk_mul_f32 v[30:31], v[42:43], s[66:67] op_sel_hi:[1,0]
	v_pk_fma_f32 v[28:29], v[102:103], v[38:39], v[28:29]
	v_pk_fma_f32 v[30:31], v[104:105], v[40:41], v[30:31]
	global_store_dwordx4 v[32:33], v[28:31], off
	s_nop 1
	v_pk_mul_f32 v[28:29], v[48:49], s[66:67] op_sel_hi:[1,0]
	v_pk_mul_f32 v[30:31], v[46:47], s[66:67] op_sel_hi:[1,0]
	v_pk_fma_f32 v[28:29], v[98:99], v[34:35], v[28:29]
	v_pk_fma_f32 v[30:31], v[100:101], v[36:37], v[30:31]
	global_store_dwordx4 v[32:33], v[28:31], off offset:16
	s_waitcnt vmcnt(16)
	v_cvt_f32_f16_e32 v34, v196
	v_cvt_f32_f16_e32 v30, v197
	v_cvt_f32_f16_sdwa v31, v197 dst_sel:DWORD dst_unused:UNUSED_PAD src0_sel:WORD_1
	v_cvt_f32_f16_sdwa v35, v196 dst_sel:DWORD dst_unused:UNUSED_PAD src0_sel:WORD_1
	v_cvt_f32_f16_e32 v26, v199
	v_cvt_f32_f16_sdwa v27, v199 dst_sel:DWORD dst_unused:UNUSED_PAD src0_sel:WORD_1
	v_cvt_f32_f16_e32 v36, v198
	v_cvt_f32_f16_sdwa v37, v198 dst_sel:DWORD dst_unused:UNUSED_PAD src0_sel:WORD_1
	v_pk_mul_f32 v[28:29], v[34:35], s[66:67] op_sel_hi:[1,0]
	v_pk_mul_f32 v[30:31], v[30:31], s[66:67] op_sel_hi:[1,0]
	v_pk_fma_f32 v[14:15], v[94:95], v[14:15], v[28:29]
	v_pk_fma_f32 v[16:17], v[96:97], v[16:17], v[30:31]
	global_store_dwordx4 v[32:33], v[14:17], off offset:512
	s_nop 1
	v_pk_mul_f32 v[14:15], v[36:37], s[66:67] op_sel_hi:[1,0]
	v_pk_mul_f32 v[16:17], v[26:27], s[66:67] op_sel_hi:[1,0]
	v_pk_fma_f32 v[10:11], v[82:83], v[10:11], v[14:15]
	v_pk_fma_f32 v[12:13], v[84:85], v[12:13], v[16:17]
	global_store_dwordx4 v[32:33], v[10:13], off offset:528
	s_nop 1
	v_lshl_add_u64 v[10:11], v[172:173], 0, s[4:5]
	v_lshl_add_u64 v[12:13], v[10:11], 1, s[22:23]
	v_lshl_add_u64 v[10:11], v[10:11], 2, s[6:7]
	s_waitcnt vmcnt(15)
	v_cvt_f32_f16_e32 v26, v215
	v_cvt_f32_f16_sdwa v27, v215 dst_sel:DWORD dst_unused:UNUSED_PAD src0_sel:WORD_1
	v_cvt_f32_f16_e32 v28, v214
	v_cvt_f32_f16_sdwa v29, v214 dst_sel:DWORD dst_unused:UNUSED_PAD src0_sel:WORD_1
	v_cvt_f32_f16_e32 v30, v217
	v_cvt_f32_f16_sdwa v31, v217 dst_sel:DWORD dst_unused:UNUSED_PAD src0_sel:WORD_1
	v_cvt_f32_f16_e32 v32, v216
	v_cvt_f32_f16_sdwa v33, v216 dst_sel:DWORD dst_unused:UNUSED_PAD src0_sel:WORD_1
	v_pk_mul_f32 v[14:15], v[28:29], s[66:67] op_sel_hi:[1,0]
	v_pk_mul_f32 v[16:17], v[26:27], s[66:67] op_sel_hi:[1,0]
	v_pk_fma_f32 v[14:15], v[102:103], v[22:23], v[14:15]
	v_pk_fma_f32 v[16:17], v[104:105], v[24:25], v[16:17]
	global_store_dwordx4 v[10:11], v[14:17], off
	s_nop 1
	v_pk_mul_f32 v[14:15], v[32:33], s[66:67] op_sel_hi:[1,0]
	v_pk_mul_f32 v[16:17], v[30:31], s[66:67] op_sel_hi:[1,0]
	v_pk_fma_f32 v[14:15], v[98:99], v[18:19], v[14:15]
	v_pk_fma_f32 v[16:17], v[100:101], v[20:21], v[16:17]
	global_store_dwordx4 v[10:11], v[14:17], off offset:16
	s_waitcnt vmcnt(14)
	v_cvt_f32_f16_e32 v18, v218
	v_cvt_f32_f16_e32 v16, v219
	v_cvt_f32_f16_sdwa v17, v219 dst_sel:DWORD dst_unused:UNUSED_PAD src0_sel:WORD_1
	v_cvt_f32_f16_sdwa v19, v218 dst_sel:DWORD dst_unused:UNUSED_PAD src0_sel:WORD_1
	v_cvt_f32_f16_e32 v12, v221
	v_cvt_f32_f16_sdwa v13, v221 dst_sel:DWORD dst_unused:UNUSED_PAD src0_sel:WORD_1
	v_cvt_f32_f16_e32 v20, v220
	v_cvt_f32_f16_sdwa v21, v220 dst_sel:DWORD dst_unused:UNUSED_PAD src0_sel:WORD_1
	v_pk_mul_f32 v[14:15], v[18:19], s[66:67] op_sel_hi:[1,0]
	v_pk_mul_f32 v[16:17], v[16:17], s[66:67] op_sel_hi:[1,0]
	v_pk_fma_f32 v[6:7], v[94:95], v[6:7], v[14:15]
	v_pk_fma_f32 v[8:9], v[96:97], v[8:9], v[16:17]
	global_store_dwordx4 v[10:11], v[6:9], off offset:512
	s_nop 1
	v_pk_mul_f32 v[6:7], v[20:21], s[66:67] op_sel_hi:[1,0]
	v_pk_mul_f32 v[8:9], v[12:13], s[66:67] op_sel_hi:[1,0]
	v_pk_fma_f32 v[2:3], v[82:83], v[2:3], v[6:7]
	v_pk_fma_f32 v[4:5], v[84:85], v[4:5], v[8:9]
	global_store_dwordx4 v[10:11], v[2:5], off offset:528

; #define GAS __attribute__((address_space(1)))
;     __device__ __forceinline__ void operator()(const f32x4 (&acc)[2][2][4][2], const Unit& u, int wr, int wc, int fr, int fq) const {
;         const int row0 = u.pm * BM + wr * 64 + fr, col0 = u.pn * BM + wc * 32 + 8 * fq;
;         const int bmod = u.pm < 4 ? 4 : ((u.pm - 4) >> 3);
;         const GAS float* gp = gate + (size_t)bmod * 12288;
;         f32x4 bv[2][2], gv[2][2];
; #pragma unroll
;         for (int bj = 0; bj < 2; ++bj)
; #pragma unroll
;             for (int n = 0; n < 2; ++n) { bv[bj][n] = *(const GAS f32x4*)(bias + col0 + bj * HALF + n * 4); gv[bj][n] = *(const GAS f32x4*)(gp + col0 + bj * HALF + n * 4); }
;         if (u.z == 0) {
; #pragma unroll
;             for (int ai = 0; ai < 2; ++ai)
; #pragma unroll
;                 for (int m = 0; m < 4; ++m) { const size_t off = (size_t)(row0 + ai * HALF + m * 16) * D + col0;
; #pragma unroll
;                     for (int bj = 0; bj < 2; ++bj) { f32x4 x0, x1; ldx8(X + off + bj * HALF, x0, x1);
;                         *(GAS f32x4*)(S + off + bj * HALF) = x0 * ALPHA + gv[bj][0] * (acc[ai][bj][m][0] + bv[bj][0]);
;                         *(GAS f32x4*)(S + off + bj * HALF + 4) = x1 * ALPHA + gv[bj][1] * (acc[ai][bj][m][1] + bv[bj][1]); } }
.LBB0_1743:
	v_lshlrev_b64 v[172:173], 11, v[176:177]
	v_lshl_add_u64 v[172:173], v[172:173], 0, v[174:175]
	v_lshl_add_u64 v[134:135], v[174:175], 2, s[44:45]
	v_lshl_add_u64 v[188:189], v[172:173], 1, s[22:23]
	global_load_dwordx4 v[122:125], v[134:135], off offset:528
	global_load_dwordx4 v[126:129], v[134:135], off offset:512
	global_load_dwordx4 v[130:133], v[134:135], off offset:16
	s_nop 0
	global_load_dwordx4 v[134:137], v[134:135], off
	s_mov_b64 s[18:19], 0x40000
	global_load_dwordx4 v[184:187], v[188:189], off
	s_waitcnt vmcnt(0)
	v_pk_add_f32 v[140:141], v[140:141], v[124:125]
	v_pk_add_f32 v[144:145], v[144:145], v[128:129]
	v_pk_add_f32 v[156:157], v[156:157], v[132:133]
	v_pk_add_f32 v[160:161], v[160:161], v[136:137]
	v_pk_add_f32 v[158:159], v[158:159], v[134:135]
	v_cvt_f32_f16_e32 v190, v185
	v_cvt_f32_f16_sdwa v191, v185 dst_sel:DWORD dst_unused:UNUSED_PAD src0_sel:WORD_1
	v_cvt_f32_f16_e32 v192, v184
	v_cvt_f32_f16_sdwa v193, v184 dst_sel:DWORD dst_unused:UNUSED_PAD src0_sel:WORD_1
	v_cvt_f32_f16_e32 v184, v187
	v_cvt_f32_f16_sdwa v185, v187 dst_sel:DWORD dst_unused:UNUSED_PAD src0_sel:WORD_1
	v_cvt_f32_f16_e32 v194, v186
	v_cvt_f32_f16_sdwa v195, v186 dst_sel:DWORD dst_unused:UNUSED_PAD src0_sel:WORD_1
	v_pk_mul_f32 v[186:187], v[192:193], s[66:67] op_sel_hi:[1,0]
	v_pk_mul_f32 v[190:191], v[190:191], s[66:67] op_sel_hi:[1,0]
	v_pk_fma_f32 v[158:159], v[102:103], v[158:159], v[186:187]
	v_pk_fma_f32 v[160:161], v[104:105], v[160:161], v[190:191]
	v_lshl_add_u64 v[186:187], v[172:173], 2, s[6:7]
	global_store_dwordx4 v[186:187], v[158:161], off
	v_pk_add_f32 v[154:155], v[154:155], v[130:131]
	v_pk_add_f32 v[142:143], v[142:143], v[126:127]
	v_pk_mul_f32 v[158:159], v[194:195], s[66:67] op_sel_hi:[1,0]
	v_pk_mul_f32 v[160:161], v[184:185], s[66:67] op_sel_hi:[1,0]
	v_pk_fma_f32 v[154:155], v[98:99], v[154:155], v[158:159]
	v_pk_fma_f32 v[156:157], v[100:101], v[156:157], v[160:161]
	global_store_dwordx4 v[186:187], v[154:157], off offset:16
	v_pk_add_f32 v[138:139], v[138:139], v[122:123]
	v_pk_add_f32 v[152:153], v[152:153], v[136:137]
	v_pk_add_f32 v[150:151], v[150:151], v[134:135]
	v_pk_add_f32 v[148:149], v[148:149], v[132:133]
	v_pk_add_f32 v[146:147], v[146:147], v[130:131]
	v_pk_add_f32 v[112:113], v[112:113], v[128:129]
	v_pk_add_f32 v[110:111], v[110:111], v[126:127]
	v_pk_add_f32 v[108:109], v[108:109], v[124:125]
	v_pk_add_f32 v[106:107], v[106:107], v[122:123]
	v_pk_add_f32 v[120:121], v[120:121], v[136:137]
	v_pk_add_f32 v[118:119], v[118:119], v[134:135]
	v_pk_add_f32 v[116:117], v[116:117], v[132:133]
	v_pk_add_f32 v[114:115], v[114:115], v[130:131]
	v_pk_add_f32 v[80:81], v[80:81], v[128:129]
	v_pk_add_f32 v[78:79], v[78:79], v[126:127]
	v_pk_add_f32 v[76:77], v[76:77], v[124:125]
	v_pk_add_f32 v[74:75], v[74:75], v[122:123]
	v_pk_add_f32 v[92:93], v[92:93], v[136:137]
	v_pk_add_f32 v[90:91], v[90:91], v[134:135]
	v_pk_add_f32 v[88:89], v[88:89], v[132:133]
	v_pk_add_f32 v[86:87], v[86:87], v[130:131]
	v_pk_add_f32 v[64:65], v[64:65], v[128:129]
	v_pk_add_f32 v[62:63], v[62:63], v[126:127]
	v_pk_add_f32 v[60:61], v[60:61], v[124:125]
	v_pk_add_f32 v[58:59], v[58:59], v[122:123]
	v_pk_add_f32 v[72:73], v[72:73], v[136:137]
	v_pk_add_f32 v[70:71], v[70:71], v[134:135]
	v_pk_add_f32 v[68:69], v[68:69], v[132:133]
	v_pk_add_f32 v[66:67], v[66:67], v[130:131]
	v_pk_add_f32 v[48:49], v[48:49], v[128:129]
	v_pk_add_f32 v[46:47], v[46:47], v[126:127]
	v_pk_add_f32 v[44:45], v[44:45], v[124:125]
	v_pk_add_f32 v[42:43], v[42:43], v[122:123]
	v_pk_add_f32 v[56:57], v[56:57], v[136:137]
	v_pk_add_f32 v[54:55], v[54:55], v[134:135]
	v_pk_add_f32 v[52:53], v[52:53], v[132:133]
	v_pk_add_f32 v[50:51], v[50:51], v[130:131]
	v_pk_add_f32 v[32:33], v[32:33], v[128:129]
	v_pk_add_f32 v[30:31], v[30:31], v[126:127]
	v_pk_add_f32 v[28:29], v[28:29], v[124:125]
	v_pk_add_f32 v[26:27], v[26:27], v[122:123]
	v_pk_add_f32 v[40:41], v[40:41], v[136:137]
	v_pk_add_f32 v[38:39], v[38:39], v[134:135]
	v_pk_add_f32 v[36:37], v[36:37], v[132:133]
	v_pk_add_f32 v[34:35], v[34:35], v[130:131]
	v_pk_add_f32 v[16:17], v[16:17], v[128:129]
	v_pk_add_f32 v[14:15], v[14:15], v[126:127]
	v_pk_add_f32 v[12:13], v[12:13], v[124:125]
	v_pk_add_f32 v[10:11], v[10:11], v[122:123]
	v_pk_add_f32 v[24:25], v[24:25], v[136:137]
	v_pk_add_f32 v[22:23], v[22:23], v[134:135]
	v_pk_add_f32 v[20:21], v[20:21], v[132:133]
	v_pk_add_f32 v[18:19], v[18:19], v[130:131]
	v_pk_add_f32 v[8:9], v[8:9], v[128:129]
	v_pk_add_f32 v[6:7], v[6:7], v[126:127]
	v_pk_add_f32 v[4:5], v[4:5], v[124:125]
	v_pk_add_f32 v[2:3], v[2:3], v[122:123]
	v_lshlrev_b32_e32 v188, 1, v172
	s_add_u32 s100, s22, 0x0
	s_addc_u32 s101, s23, 0
	global_load_dwordx4 v[124:127], v188, s[100:101] offset:256
	s_add_u32 s100, s22, 0x10000
	s_addc_u32 s101, s23, 0
	global_load_dwordx4 v[128:131], v188, s[100:101]
	s_add_u32 s100, s22, 0x10000
	s_addc_u32 s101, s23, 0
	global_load_dwordx4 v[132:135], v188, s[100:101] offset:256
	s_add_u32 s100, s22, 0x20000
	s_addc_u32 s101, s23, 0
	global_load_dwordx4 v[192:195], v188, s[100:101]
	s_add_u32 s100, s22, 0x20000
	s_addc_u32 s101, s23, 0
	global_load_dwordx4 v[196:199], v188, s[100:101] offset:256
	s_add_u32 s100, s22, 0x30000
	s_addc_u32 s101, s23, 0
	global_load_dwordx4 v[214:217], v188, s[100:101]
	s_add_u32 s100, s22, 0x30000
	s_addc_u32 s101, s23, 0
	global_load_dwordx4 v[218:221], v188, s[100:101] offset:256
	s_add_u32 s100, s22, 0x80000
	s_addc_u32 s101, s23, 0
	global_load_dwordx4 v[222:225], v188, s[100:101]
	s_waitcnt vmcnt(7)
; #define GAS __attribute__((address_space(1)))
; __device__ __forceinline__ void ldx8(const GAS f16_t* p, f32x4& lo, f32x4& hi) { const f16x8 h = *(const GAS f16x8*)p;
;     lo = __builtin_convertvector(__builtin_shufflevector(h, h, 0, 1, 2, 3), f32x4); hi = __builtin_convertvector(__builtin_shufflevector(h, h, 4, 5, 6, 7), f32x4); }
;     __device__ __forceinline__ void operator()(const f32x4 (&acc)[2][2][4][2], const Unit& u, int wr, int wc, int fr, int fq) const {
;     ...
;                 for (int m = 0; m < 4; ++m) { const size_t off = (size_t)(row0 + ai * HALF + m * 16) * D + col0;
; #pragma unroll
;                     for (int bj = 0; bj < 2; ++bj) { f32x4 x0, x1; ldx8(X + off + bj * HALF, x0, x1);
;                         *(GAS f32x4*)(S + off + bj * HALF) = x0 * ALPHA + gv[bj][0] * (acc[ai][bj][m][0] + bv[bj][0]);
;                         *(GAS f32x4*)(S + off + bj * HALF + 4) = x1 * ALPHA + gv[bj][1] * (acc[ai][bj][m][1] + bv[bj][1]); } }
	v_cvt_f32_f16_e32 v158, v125
	v_cvt_f32_f16_sdwa v159, v125 dst_sel:DWORD dst_unused:UNUSED_PAD src0_sel:WORD_1
	v_cvt_f32_f16_e32 v160, v124
	v_cvt_f32_f16_sdwa v161, v124 dst_sel:DWORD dst_unused:UNUSED_PAD src0_sel:WORD_1
	v_cvt_f32_f16_e32 v154, v127
	v_cvt_f32_f16_sdwa v155, v127 dst_sel:DWORD dst_unused:UNUSED_PAD src0_sel:WORD_1
	v_cvt_f32_f16_e32 v184, v126
	v_cvt_f32_f16_sdwa v185, v126 dst_sel:DWORD dst_unused:UNUSED_PAD src0_sel:WORD_1
	v_pk_mul_f32 v[156:157], v[160:161], s[66:67] op_sel_hi:[1,0]
	v_pk_mul_f32 v[158:159], v[158:159], s[66:67] op_sel_hi:[1,0]
	v_pk_fma_f32 v[142:143], v[94:95], v[142:143], v[156:157]
	v_pk_fma_f32 v[144:145], v[96:97], v[144:145], v[158:159]
	global_store_dwordx4 v[186:187], v[142:145], off offset:512
	s_nop 1
	v_pk_mul_f32 v[142:143], v[184:185], s[66:67] op_sel_hi:[1,0]
	v_pk_mul_f32 v[144:145], v[154:155], s[66:67] op_sel_hi:[1,0]
	v_pk_fma_f32 v[138:139], v[82:83], v[138:139], v[142:143]
	v_pk_fma_f32 v[140:141], v[84:85], v[140:141], v[144:145]
	global_store_dwordx4 v[186:187], v[138:141], off offset:528
	s_nop 1
	v_or_b32_e32 v138, 16, v176
	v_ashrrev_i32_e32 v139, 31, v138
	v_lshlrev_b64 v[138:139], 11, v[138:139]
	v_lshl_add_u64 v[144:145], v[138:139], 0, v[174:175]
	v_lshl_add_u64 v[138:139], v[144:145], 1, s[22:23]
	s_add_u32 s100, s22, 0x80000
	s_addc_u32 s101, s23, 0
	global_load_dwordx4 v[124:127], v188, s[100:101] offset:256
	v_lshl_add_u64 v[144:145], v[144:145], 2, s[6:7]
	s_waitcnt vmcnt(9)
	v_cvt_f32_f16_e32 v154, v129
	v_cvt_f32_f16_sdwa v155, v129 dst_sel:DWORD dst_unused:UNUSED_PAD src0_sel:WORD_1
	v_cvt_f32_f16_e32 v156, v128
	v_cvt_f32_f16_sdwa v157, v128 dst_sel:DWORD dst_unused:UNUSED_PAD src0_sel:WORD_1
	v_cvt_f32_f16_e32 v158, v131
	v_cvt_f32_f16_sdwa v159, v131 dst_sel:DWORD dst_unused:UNUSED_PAD src0_sel:WORD_1
	v_cvt_f32_f16_e32 v160, v130
	v_cvt_f32_f16_sdwa v161, v130 dst_sel:DWORD dst_unused:UNUSED_PAD src0_sel:WORD_1
	v_pk_mul_f32 v[140:141], v[156:157], s[66:67] op_sel_hi:[1,0]
	v_pk_mul_f32 v[142:143], v[154:155], s[66:67] op_sel_hi:[1,0]
	v_pk_fma_f32 v[140:141], v[102:103], v[150:151], v[140:141]
	v_pk_fma_f32 v[142:143], v[104:105], v[152:153], v[142:143]
	global_store_dwordx4 v[144:145], v[140:143], off
	s_nop 1
	v_pk_mul_f32 v[140:141], v[160:161], s[66:67] op_sel_hi:[1,0]
	v_pk_mul_f32 v[142:143], v[158:159], s[66:67] op_sel_hi:[1,0]
	v_pk_fma_f32 v[140:141], v[98:99], v[146:147], v[140:141]
	v_pk_fma_f32 v[142:143], v[100:101], v[148:149], v[142:143]
	global_store_dwordx4 v[144:145], v[140:143], off offset:16
	s_add_u32 s100, s22, 0x90000
	s_addc_u32 s101, s23, 0
	global_load_dwordx4 v[128:131], v188, s[100:101]
	s_waitcnt vmcnt(11)
	v_cvt_f32_f16_e32 v146, v132
	v_cvt_f32_f16_e32 v142, v133
	v_cvt_f32_f16_sdwa v143, v133 dst_sel:DWORD dst_unused:UNUSED_PAD src0_sel:WORD_1
	v_cvt_f32_f16_sdwa v147, v132 dst_sel:DWORD dst_unused:UNUSED_PAD src0_sel:WORD_1
	v_cvt_f32_f16_e32 v138, v135
	v_cvt_f32_f16_sdwa v139, v135 dst_sel:DWORD dst_unused:UNUSED_PAD src0_sel:WORD_1
	v_cvt_f32_f16_e32 v148, v134
	v_cvt_f32_f16_sdwa v149, v134 dst_sel:DWORD dst_unused:UNUSED_PAD src0_sel:WORD_1
	v_pk_mul_f32 v[140:141], v[146:147], s[66:67] op_sel_hi:[1,0]
	v_pk_mul_f32 v[142:143], v[142:143], s[66:67] op_sel_hi:[1,0]
	v_pk_fma_f32 v[110:111], v[94:95], v[110:111], v[140:141]
	v_pk_fma_f32 v[112:113], v[96:97], v[112:113], v[142:143]
	global_store_dwordx4 v[144:145], v[110:113], off offset:512
	s_nop 1
	v_pk_mul_f32 v[110:111], v[148:149], s[66:67] op_sel_hi:[1,0]
	v_pk_mul_f32 v[112:113], v[138:139], s[66:67] op_sel_hi:[1,0]
	v_pk_fma_f32 v[106:107], v[82:83], v[106:107], v[110:111]
	v_pk_fma_f32 v[108:109], v[84:85], v[108:109], v[112:113]
	global_store_dwordx4 v[144:145], v[106:109], off offset:528
	s_nop 1
	v_or_b32_e32 v106, 32, v176
	v_ashrrev_i32_e32 v107, 31, v106
	v_lshlrev_b64 v[106:107], 11, v[106:107]
	v_lshl_add_u64 v[112:113], v[106:107], 0, v[174:175]
	v_lshl_add_u64 v[106:107], v[112:113], 1, s[22:23]
	s_add_u32 s100, s22, 0x90000
	s_addc_u32 s101, s23, 0
	global_load_dwordx4 v[132:135], v188, s[100:101] offset:256
	v_lshl_add_u64 v[112:113], v[112:113], 2, s[6:7]
	s_waitcnt vmcnt(13)
	v_cvt_f32_f16_e32 v138, v193
	v_cvt_f32_f16_sdwa v139, v193 dst_sel:DWORD dst_unused:UNUSED_PAD src0_sel:WORD_1
	v_cvt_f32_f16_e32 v140, v192
	v_cvt_f32_f16_sdwa v141, v192 dst_sel:DWORD dst_unused:UNUSED_PAD src0_sel:WORD_1
	v_cvt_f32_f16_e32 v142, v195
	v_cvt_f32_f16_sdwa v143, v195 dst_sel:DWORD dst_unused:UNUSED_PAD src0_sel:WORD_1
	v_cvt_f32_f16_e32 v144, v194
	v_cvt_f32_f16_sdwa v145, v194 dst_sel:DWORD dst_unused:UNUSED_PAD src0_sel:WORD_1
	v_pk_mul_f32 v[108:109], v[140:141], s[66:67] op_sel_hi:[1,0]
	v_pk_mul_f32 v[110:111], v[138:139], s[66:67] op_sel_hi:[1,0]
	v_pk_fma_f32 v[108:109], v[102:103], v[118:119], v[108:109]
	v_pk_fma_f32 v[110:111], v[104:105], v[120:121], v[110:111]
	global_store_dwordx4 v[112:113], v[108:111], off
	s_nop 1
	v_pk_mul_f32 v[108:109], v[144:145], s[66:67] op_sel_hi:[1,0]
	v_pk_mul_f32 v[110:111], v[142:143], s[66:67] op_sel_hi:[1,0]
	v_pk_fma_f32 v[108:109], v[98:99], v[114:115], v[108:109]
	v_pk_fma_f32 v[110:111], v[100:101], v[116:117], v[110:111]
	global_store_dwordx4 v[112:113], v[108:111], off offset:16
	s_add_u32 s100, s22, 0xa0000
	s_addc_u32 s101, s23, 0
	global_load_dwordx4 v[192:195], v188, s[100:101]
	s_waitcnt vmcnt(15)
; #define GAS __attribute__((address_space(1)))
; __device__ __forceinline__ void ldx8(const GAS f16_t* p, f32x4& lo, f32x4& hi) { const f16x8 h = *(const GAS f16x8*)p;
;     lo = __builtin_convertvector(__builtin_shufflevector(h, h, 0, 1, 2, 3), f32x4); hi = __builtin_convertvector(__builtin_shufflevector(h, h, 4, 5, 6, 7), f32x4); }
;     __device__ __forceinline__ void operator()(const f32x4 (&acc)[2][2][4][2], const Unit& u, int wr, int wc, int fr, int fq) const {
;     ...
;                 for (int m = 0; m < 4; ++m) { const size_t off = (size_t)(row0 + ai * HALF + m * 16) * D + col0;
; #pragma unroll
;                     for (int bj = 0; bj < 2; ++bj) { f32x4 x0, x1; ldx8(X + off + bj * HALF, x0, x1);
;                         *(GAS f32x4*)(S + off + bj * HALF) = x0 * ALPHA + gv[bj][0] * (acc[ai][bj][m][0] + bv[bj][0]);
;                         *(GAS f32x4*)(S + off + bj * HALF + 4) = x1 * ALPHA + gv[bj][1] * (acc[ai][bj][m][1] + bv[bj][1]); } }
	v_cvt_f32_f16_e32 v114, v196
	v_cvt_f32_f16_e32 v110, v197
	v_cvt_f32_f16_sdwa v111, v197 dst_sel:DWORD dst_unused:UNUSED_PAD src0_sel:WORD_1
	v_cvt_f32_f16_sdwa v115, v196 dst_sel:DWORD dst_unused:UNUSED_PAD src0_sel:WORD_1
	v_cvt_f32_f16_e32 v106, v199
	v_cvt_f32_f16_sdwa v107, v199 dst_sel:DWORD dst_unused:UNUSED_PAD src0_sel:WORD_1
	v_cvt_f32_f16_e32 v116, v198
	v_cvt_f32_f16_sdwa v117, v198 dst_sel:DWORD dst_unused:UNUSED_PAD src0_sel:WORD_1
	v_pk_mul_f32 v[108:109], v[114:115], s[66:67] op_sel_hi:[1,0]
	v_pk_mul_f32 v[110:111], v[110:111], s[66:67] op_sel_hi:[1,0]
	v_pk_fma_f32 v[78:79], v[94:95], v[78:79], v[108:109]
	v_pk_fma_f32 v[80:81], v[96:97], v[80:81], v[110:111]
	global_store_dwordx4 v[112:113], v[78:81], off offset:512
	s_nop 1
	v_pk_mul_f32 v[78:79], v[116:117], s[66:67] op_sel_hi:[1,0]
	v_pk_mul_f32 v[80:81], v[106:107], s[66:67] op_sel_hi:[1,0]
	v_pk_fma_f32 v[74:75], v[82:83], v[74:75], v[78:79]
	v_pk_fma_f32 v[76:77], v[84:85], v[76:77], v[80:81]
	global_store_dwordx4 v[112:113], v[74:77], off offset:528
	s_nop 1
	v_or_b32_e32 v74, 48, v176
	v_ashrrev_i32_e32 v75, 31, v74
	v_lshlrev_b64 v[74:75], 11, v[74:75]
	v_lshl_add_u64 v[80:81], v[74:75], 0, v[174:175]
	v_lshl_add_u64 v[74:75], v[80:81], 1, s[22:23]
	s_add_u32 s100, s22, 0xa0000
	s_addc_u32 s101, s23, 0
	global_load_dwordx4 v[196:199], v188, s[100:101] offset:256
	v_lshl_add_u64 v[80:81], v[80:81], 2, s[6:7]
	s_waitcnt vmcnt(17)
	v_cvt_f32_f16_e32 v106, v215
	v_cvt_f32_f16_sdwa v107, v215 dst_sel:DWORD dst_unused:UNUSED_PAD src0_sel:WORD_1
	v_cvt_f32_f16_e32 v108, v214
	v_cvt_f32_f16_sdwa v109, v214 dst_sel:DWORD dst_unused:UNUSED_PAD src0_sel:WORD_1
	v_cvt_f32_f16_e32 v110, v217
	v_cvt_f32_f16_sdwa v111, v217 dst_sel:DWORD dst_unused:UNUSED_PAD src0_sel:WORD_1
	v_cvt_f32_f16_e32 v112, v216
	v_cvt_f32_f16_sdwa v113, v216 dst_sel:DWORD dst_unused:UNUSED_PAD src0_sel:WORD_1
	v_pk_mul_f32 v[76:77], v[108:109], s[66:67] op_sel_hi:[1,0]
	v_pk_mul_f32 v[78:79], v[106:107], s[66:67] op_sel_hi:[1,0]
	v_pk_fma_f32 v[76:77], v[102:103], v[90:91], v[76:77]
	v_pk_fma_f32 v[78:79], v[104:105], v[92:93], v[78:79]
	global_store_dwordx4 v[80:81], v[76:79], off
	s_nop 1
	v_pk_mul_f32 v[76:77], v[112:113], s[66:67] op_sel_hi:[1,0]
	v_pk_mul_f32 v[78:79], v[110:111], s[66:67] op_sel_hi:[1,0]
	v_pk_fma_f32 v[76:77], v[98:99], v[86:87], v[76:77]
	v_pk_fma_f32 v[78:79], v[100:101], v[88:89], v[78:79]
	global_store_dwordx4 v[80:81], v[76:79], off offset:16
	s_add_u32 s100, s22, 0xb0000
	s_addc_u32 s101, s23, 0
	global_load_dwordx4 v[214:217], v188, s[100:101]
	s_waitcnt vmcnt(19)
	v_cvt_f32_f16_e32 v86, v218
	v_cvt_f32_f16_e32 v78, v219
	v_cvt_f32_f16_sdwa v79, v219 dst_sel:DWORD dst_unused:UNUSED_PAD src0_sel:WORD_1
	v_cvt_f32_f16_sdwa v87, v218 dst_sel:DWORD dst_unused:UNUSED_PAD src0_sel:WORD_1
	v_cvt_f32_f16_e32 v74, v221
	v_cvt_f32_f16_sdwa v75, v221 dst_sel:DWORD dst_unused:UNUSED_PAD src0_sel:WORD_1
	v_cvt_f32_f16_e32 v88, v220
	v_cvt_f32_f16_sdwa v89, v220 dst_sel:DWORD dst_unused:UNUSED_PAD src0_sel:WORD_1
	v_pk_mul_f32 v[76:77], v[86:87], s[66:67] op_sel_hi:[1,0]
	v_pk_mul_f32 v[78:79], v[78:79], s[66:67] op_sel_hi:[1,0]
	v_pk_fma_f32 v[62:63], v[94:95], v[62:63], v[76:77]
	v_pk_fma_f32 v[64:65], v[96:97], v[64:65], v[78:79]
	global_store_dwordx4 v[80:81], v[62:65], off offset:512
	s_nop 1
	v_pk_mul_f32 v[62:63], v[88:89], s[66:67] op_sel_hi:[1,0]
	v_pk_mul_f32 v[64:65], v[74:75], s[66:67] op_sel_hi:[1,0]
	v_pk_fma_f32 v[58:59], v[82:83], v[58:59], v[62:63]
	v_pk_fma_f32 v[60:61], v[84:85], v[60:61], v[64:65]
	v_lshl_add_u64 v[64:65], v[172:173], 0, s[18:19]
	global_store_dwordx4 v[80:81], v[58:61], off offset:528
	s_mov_b64 s[18:19], 0x48000
	s_nop 0
	v_lshl_add_u64 v[58:59], v[64:65], 1, s[22:23]
	s_add_u32 s100, s22, 0xb0000
	s_addc_u32 s101, s23, 0
	global_load_dwordx4 v[218:221], v188, s[100:101] offset:256
	v_lshl_add_u64 v[64:65], v[64:65], 2, s[6:7]
	s_waitcnt vmcnt(21)
	v_cvt_f32_f16_e32 v74, v223
	v_cvt_f32_f16_sdwa v75, v223 dst_sel:DWORD dst_unused:UNUSED_PAD src0_sel:WORD_1
	v_cvt_f32_f16_e32 v76, v222
	v_cvt_f32_f16_sdwa v77, v222 dst_sel:DWORD dst_unused:UNUSED_PAD src0_sel:WORD_1
	v_cvt_f32_f16_e32 v78, v225
	v_cvt_f32_f16_sdwa v79, v225 dst_sel:DWORD dst_unused:UNUSED_PAD src0_sel:WORD_1
	v_cvt_f32_f16_e32 v80, v224
	v_cvt_f32_f16_sdwa v81, v224 dst_sel:DWORD dst_unused:UNUSED_PAD src0_sel:WORD_1
	v_pk_mul_f32 v[60:61], v[76:77], s[66:67] op_sel_hi:[1,0]
	v_pk_mul_f32 v[62:63], v[74:75], s[66:67] op_sel_hi:[1,0]
	v_pk_fma_f32 v[60:61], v[102:103], v[70:71], v[60:61]
	v_pk_fma_f32 v[62:63], v[104:105], v[72:73], v[62:63]
	global_store_dwordx4 v[64:65], v[60:63], off
	s_nop 1
	v_pk_mul_f32 v[60:61], v[80:81], s[66:67] op_sel_hi:[1,0]
	v_pk_mul_f32 v[62:63], v[78:79], s[66:67] op_sel_hi:[1,0]
	v_pk_fma_f32 v[60:61], v[98:99], v[66:67], v[60:61]
	v_pk_fma_f32 v[62:63], v[100:101], v[68:69], v[62:63]
	global_store_dwordx4 v[64:65], v[60:63], off offset:16
	s_waitcnt vmcnt(20)
	v_cvt_f32_f16_e32 v66, v124
	v_cvt_f32_f16_e32 v62, v125
	v_cvt_f32_f16_sdwa v63, v125 dst_sel:DWORD dst_unused:UNUSED_PAD src0_sel:WORD_1
	v_cvt_f32_f16_sdwa v67, v124 dst_sel:DWORD dst_unused:UNUSED_PAD src0_sel:WORD_1
	v_cvt_f32_f16_e32 v58, v127
	v_cvt_f32_f16_sdwa v59, v127 dst_sel:DWORD dst_unused:UNUSED_PAD src0_sel:WORD_1
	v_cvt_f32_f16_e32 v68, v126
	v_cvt_f32_f16_sdwa v69, v126 dst_sel:DWORD dst_unused:UNUSED_PAD src0_sel:WORD_1
	v_pk_mul_f32 v[60:61], v[66:67], s[66:67] op_sel_hi:[1,0]
	v_pk_mul_f32 v[62:63], v[62:63], s[66:67] op_sel_hi:[1,0]
	v_pk_fma_f32 v[46:47], v[94:95], v[46:47], v[60:61]
	v_pk_fma_f32 v[48:49], v[96:97], v[48:49], v[62:63]
	global_store_dwordx4 v[64:65], v[46:49], off offset:512
	s_nop 1
	v_pk_mul_f32 v[46:47], v[68:69], s[66:67] op_sel_hi:[1,0]
	v_pk_mul_f32 v[48:49], v[58:59], s[66:67] op_sel_hi:[1,0]
	v_pk_fma_f32 v[42:43], v[82:83], v[42:43], v[46:47]
	v_pk_fma_f32 v[44:45], v[84:85], v[44:45], v[48:49]
	v_lshl_add_u64 v[48:49], v[172:173], 0, s[18:19]
	global_store_dwordx4 v[64:65], v[42:45], off offset:528
	s_mov_b64 s[18:19], 0x50000
	s_nop 0
	v_lshl_add_u64 v[42:43], v[48:49], 1, s[22:23]
	v_lshl_add_u64 v[48:49], v[48:49], 2, s[6:7]
	s_waitcnt vmcnt(19)
; #define GAS __attribute__((address_space(1)))
;     __device__ __forceinline__ void operator()(const f32x4 (&acc)[2][2][4][2], const Unit& u, int wr, int wc, int fr, int fq) const {
;     ...
;                 for (int m = 0; m < 4; ++m) { const size_t off = (size_t)(row0 + ai * HALF + m * 16) * D + col0;
; #pragma unroll
;                     for (int bj = 0; bj < 2; ++bj) { f32x4 x0, x1; ldx8(X + off + bj * HALF, x0, x1);
;                         *(GAS f32x4*)(S + off + bj * HALF) = x0 * ALPHA + gv[bj][0] * (acc[ai][bj][m][0] + bv[bj][0]);
;                         *(GAS f32x4*)(S + off + bj * HALF + 4) = x1 * ALPHA + gv[bj][1] * (acc[ai][bj][m][1] + bv[bj][1]); } }
	v_cvt_f32_f16_e32 v58, v129
	v_cvt_f32_f16_sdwa v59, v129 dst_sel:DWORD dst_unused:UNUSED_PAD src0_sel:WORD_1
	v_cvt_f32_f16_e32 v60, v128
	v_cvt_f32_f16_sdwa v61, v128 dst_sel:DWORD dst_unused:UNUSED_PAD src0_sel:WORD_1
	v_cvt_f32_f16_e32 v62, v131
	v_cvt_f32_f16_sdwa v63, v131 dst_sel:DWORD dst_unused:UNUSED_PAD src0_sel:WORD_1
	v_cvt_f32_f16_e32 v64, v130
	v_cvt_f32_f16_sdwa v65, v130 dst_sel:DWORD dst_unused:UNUSED_PAD src0_sel:WORD_1
	v_pk_mul_f32 v[44:45], v[60:61], s[66:67] op_sel_hi:[1,0]
	v_pk_mul_f32 v[46:47], v[58:59], s[66:67] op_sel_hi:[1,0]
	v_pk_fma_f32 v[44:45], v[102:103], v[54:55], v[44:45]
	v_pk_fma_f32 v[46:47], v[104:105], v[56:57], v[46:47]
	global_store_dwordx4 v[48:49], v[44:47], off
	s_nop 1
	v_pk_mul_f32 v[44:45], v[64:65], s[66:67] op_sel_hi:[1,0]
	v_pk_mul_f32 v[46:47], v[62:63], s[66:67] op_sel_hi:[1,0]
	v_pk_fma_f32 v[44:45], v[98:99], v[50:51], v[44:45]
	v_pk_fma_f32 v[46:47], v[100:101], v[52:53], v[46:47]
	global_store_dwordx4 v[48:49], v[44:47], off offset:16
	s_waitcnt vmcnt(18)
	v_cvt_f32_f16_e32 v50, v132
	v_cvt_f32_f16_e32 v46, v133
	v_cvt_f32_f16_sdwa v47, v133 dst_sel:DWORD dst_unused:UNUSED_PAD src0_sel:WORD_1
	v_cvt_f32_f16_sdwa v51, v132 dst_sel:DWORD dst_unused:UNUSED_PAD src0_sel:WORD_1
	v_cvt_f32_f16_e32 v42, v135
	v_cvt_f32_f16_sdwa v43, v135 dst_sel:DWORD dst_unused:UNUSED_PAD src0_sel:WORD_1
	v_cvt_f32_f16_e32 v52, v134
	v_cvt_f32_f16_sdwa v53, v134 dst_sel:DWORD dst_unused:UNUSED_PAD src0_sel:WORD_1
	v_pk_mul_f32 v[44:45], v[50:51], s[66:67] op_sel_hi:[1,0]
	v_pk_mul_f32 v[46:47], v[46:47], s[66:67] op_sel_hi:[1,0]
	v_pk_fma_f32 v[30:31], v[94:95], v[30:31], v[44:45]
	v_pk_fma_f32 v[32:33], v[96:97], v[32:33], v[46:47]
	global_store_dwordx4 v[48:49], v[30:33], off offset:512
	s_nop 1
	v_pk_mul_f32 v[30:31], v[52:53], s[66:67] op_sel_hi:[1,0]
	v_pk_mul_f32 v[32:33], v[42:43], s[66:67] op_sel_hi:[1,0]
	v_pk_fma_f32 v[26:27], v[82:83], v[26:27], v[30:31]
	v_pk_fma_f32 v[28:29], v[84:85], v[28:29], v[32:33]
	v_lshl_add_u64 v[32:33], v[172:173], 0, s[18:19]
	global_store_dwordx4 v[48:49], v[26:29], off offset:528
	s_mov_b64 s[18:19], 0x58000
	s_nop 0
	v_lshl_add_u64 v[26:27], v[32:33], 1, s[22:23]
	v_lshl_add_u64 v[32:33], v[32:33], 2, s[6:7]
	s_waitcnt vmcnt(17)
	v_cvt_f32_f16_e32 v42, v193
	v_cvt_f32_f16_sdwa v43, v193 dst_sel:DWORD dst_unused:UNUSED_PAD src0_sel:WORD_1
	v_cvt_f32_f16_e32 v44, v192
	v_cvt_f32_f16_sdwa v45, v192 dst_sel:DWORD dst_unused:UNUSED_PAD src0_sel:WORD_1
	v_cvt_f32_f16_e32 v46, v195
	v_cvt_f32_f16_sdwa v47, v195 dst_sel:DWORD dst_unused:UNUSED_PAD src0_sel:WORD_1
	v_cvt_f32_f16_e32 v48, v194
	v_cvt_f32_f16_sdwa v49, v194 dst_sel:DWORD dst_unused:UNUSED_PAD src0_sel:WORD_1
	v_pk_mul_f32 v[28:29], v[44:45], s[66:67] op_sel_hi:[1,0]
	v_pk_mul_f32 v[30:31], v[42:43], s[66:67] op_sel_hi:[1,0]
	v_pk_fma_f32 v[28:29], v[102:103], v[38:39], v[28:29]
	v_pk_fma_f32 v[30:31], v[104:105], v[40:41], v[30:31]
	global_store_dwordx4 v[32:33], v[28:31], off
	s_nop 1
	v_pk_mul_f32 v[28:29], v[48:49], s[66:67] op_sel_hi:[1,0]
	v_pk_mul_f32 v[30:31], v[46:47], s[66:67] op_sel_hi:[1,0]
	v_pk_fma_f32 v[28:29], v[98:99], v[34:35], v[28:29]
	v_pk_fma_f32 v[30:31], v[100:101], v[36:37], v[30:31]
	global_store_dwordx4 v[32:33], v[28:31], off offset:16
	s_waitcnt vmcnt(16)
	v_cvt_f32_f16_e32 v34, v196
	v_cvt_f32_f16_e32 v30, v197
	v_cvt_f32_f16_sdwa v31, v197 dst_sel:DWORD dst_unused:UNUSED_PAD src0_sel:WORD_1
	v_cvt_f32_f16_sdwa v35, v196 dst_sel:DWORD dst_unused:UNUSED_PAD src0_sel:WORD_1
	v_cvt_f32_f16_e32 v26, v199
	v_cvt_f32_f16_sdwa v27, v199 dst_sel:DWORD dst_unused:UNUSED_PAD src0_sel:WORD_1
	v_cvt_f32_f16_e32 v36, v198
	v_cvt_f32_f16_sdwa v37, v198 dst_sel:DWORD dst_unused:UNUSED_PAD src0_sel:WORD_1
	v_pk_mul_f32 v[28:29], v[34:35], s[66:67] op_sel_hi:[1,0]
	v_pk_mul_f32 v[30:31], v[30:31], s[66:67] op_sel_hi:[1,0]
	v_pk_fma_f32 v[14:15], v[94:95], v[14:15], v[28:29]
	v_pk_fma_f32 v[16:17], v[96:97], v[16:17], v[30:31]
	global_store_dwordx4 v[32:33], v[14:17], off offset:512
	s_nop 1
	v_pk_mul_f32 v[14:15], v[36:37], s[66:67] op_sel_hi:[1,0]
	v_pk_mul_f32 v[16:17], v[26:27], s[66:67] op_sel_hi:[1,0]
	v_pk_fma_f32 v[10:11], v[82:83], v[10:11], v[14:15]
	v_pk_fma_f32 v[12:13], v[84:85], v[12:13], v[16:17]
	global_store_dwordx4 v[32:33], v[10:13], off offset:528
	s_nop 1
	v_lshl_add_u64 v[10:11], v[172:173], 0, s[18:19]
	v_lshl_add_u64 v[12:13], v[10:11], 1, s[22:23]
	v_lshl_add_u64 v[10:11], v[10:11], 2, s[6:7]
	s_waitcnt vmcnt(15)
	v_cvt_f32_f16_e32 v26, v215
	v_cvt_f32_f16_sdwa v27, v215 dst_sel:DWORD dst_unused:UNUSED_PAD src0_sel:WORD_1
	v_cvt_f32_f16_e32 v28, v214
	v_cvt_f32_f16_sdwa v29, v214 dst_sel:DWORD dst_unused:UNUSED_PAD src0_sel:WORD_1
	v_cvt_f32_f16_e32 v30, v217
	v_cvt_f32_f16_sdwa v31, v217 dst_sel:DWORD dst_unused:UNUSED_PAD src0_sel:WORD_1
	v_cvt_f32_f16_e32 v32, v216
	v_cvt_f32_f16_sdwa v33, v216 dst_sel:DWORD dst_unused:UNUSED_PAD src0_sel:WORD_1
	v_pk_mul_f32 v[14:15], v[28:29], s[66:67] op_sel_hi:[1,0]
	v_pk_mul_f32 v[16:17], v[26:27], s[66:67] op_sel_hi:[1,0]
	v_pk_fma_f32 v[14:15], v[102:103], v[22:23], v[14:15]
	v_pk_fma_f32 v[16:17], v[104:105], v[24:25], v[16:17]
	global_store_dwordx4 v[10:11], v[14:17], off
	s_nop 1
	v_pk_mul_f32 v[14:15], v[32:33], s[66:67] op_sel_hi:[1,0]
	v_pk_mul_f32 v[16:17], v[30:31], s[66:67] op_sel_hi:[1,0]
	v_pk_fma_f32 v[14:15], v[98:99], v[18:19], v[14:15]
	v_pk_fma_f32 v[16:17], v[100:101], v[20:21], v[16:17]
	global_store_dwordx4 v[10:11], v[14:17], off offset:16
	s_waitcnt vmcnt(14)
	v_cvt_f32_f16_e32 v18, v218
	v_cvt_f32_f16_e32 v16, v219
	v_cvt_f32_f16_sdwa v17, v219 dst_sel:DWORD dst_unused:UNUSED_PAD src0_sel:WORD_1
	v_cvt_f32_f16_sdwa v19, v218 dst_sel:DWORD dst_unused:UNUSED_PAD src0_sel:WORD_1
	v_cvt_f32_f16_e32 v12, v221
	v_cvt_f32_f16_sdwa v13, v221 dst_sel:DWORD dst_unused:UNUSED_PAD src0_sel:WORD_1
	v_cvt_f32_f16_e32 v20, v220
	v_cvt_f32_f16_sdwa v21, v220 dst_sel:DWORD dst_unused:UNUSED_PAD src0_sel:WORD_1
	v_pk_mul_f32 v[14:15], v[18:19], s[66:67] op_sel_hi:[1,0]
	v_pk_mul_f32 v[16:17], v[16:17], s[66:67] op_sel_hi:[1,0]
	v_pk_fma_f32 v[6:7], v[94:95], v[6:7], v[14:15]
	v_pk_fma_f32 v[8:9], v[96:97], v[8:9], v[16:17]
	global_store_dwordx4 v[10:11], v[6:9], off offset:512
	s_nop 1
	v_pk_mul_f32 v[6:7], v[20:21], s[66:67] op_sel_hi:[1,0]
	v_pk_mul_f32 v[8:9], v[12:13], s[66:67] op_sel_hi:[1,0]
	v_pk_fma_f32 v[2:3], v[82:83], v[2:3], v[6:7]
	v_pk_fma_f32 v[4:5], v[84:85], v[4:5], v[8:9]
	global_store_dwordx4 v[10:11], v[2:5], off offset:528
